# v86: grid-barrier poll loop (7 sites): the 16 arrival-counter loads issued back to back, adds behind counted waits (protocol unchanged)
# baseline (speedup 1.0000x reference)
.LBB0_254:
	v_readlane_b32 s6, v253, 13
	v_readlane_b32 s7, v253, 14
	global_load_dword v0, v1, s[30:31] sc1
	s_mov_b64 s[8:9], -1
	s_waitcnt lgkmcnt(0)
	s_nop 1
	global_load_dword v2, v1, s[6:7] sc1
	v_readlane_b32 s6, v253, 15
	v_readlane_b32 s7, v253, 16
	s_nop 4
	global_load_dword v3, v1, s[6:7] sc1
	v_readlane_b32 s6, v253, 17
	v_readlane_b32 s7, v253, 18
	s_nop 4
	global_load_dword v4, v1, s[6:7] sc1
	v_readlane_b32 s6, v253, 19
	v_readlane_b32 s7, v253, 20
	s_nop 4
	global_load_dword v5, v1, s[6:7] sc1
	v_readlane_b32 s6, v253, 21
	v_readlane_b32 s7, v253, 22
	s_nop 4
	global_load_dword v6, v1, s[6:7] sc1
	v_readlane_b32 s6, v253, 23
	v_readlane_b32 s7, v253, 24
	s_nop 4
	global_load_dword v7, v1, s[6:7] sc1
	v_readlane_b32 s6, v253, 25
	v_readlane_b32 s7, v253, 26
	s_nop 4
	global_load_dword v8, v1, s[6:7] sc1
	v_readlane_b32 s6, v253, 27
	v_readlane_b32 s7, v253, 28
	s_nop 4
	global_load_dword v9, v1, s[6:7] sc1
	v_readlane_b32 s6, v253, 29
	v_readlane_b32 s7, v253, 30
	s_nop 4
	global_load_dword v10, v1, s[6:7] sc1
	v_readlane_b32 s6, v253, 31
	v_readlane_b32 s7, v253, 32
	s_nop 4
	global_load_dword v11, v1, s[6:7] sc1
	v_readlane_b32 s6, v253, 33
	v_readlane_b32 s7, v253, 34
	s_nop 4
	global_load_dword v12, v1, s[6:7] sc1
	v_readlane_b32 s6, v253, 35
	v_readlane_b32 s7, v253, 36
	s_nop 4
	global_load_dword v13, v1, s[6:7] sc1
	global_load_dword v14, v1, s[90:91] sc1
	global_load_dword v15, v1, s[92:93] sc1
	global_load_dword v16, v1, s[94:95] sc1
	s_mov_b64 s[6:7], -1
	s_waitcnt vmcnt(5)
	v_add_u32_e32 v17, v2, v0
	v_add_u32_e32 v17, v17, v3
	v_add_u32_e32 v17, v17, v4
	v_add_u32_e32 v17, v17, v5
	v_add_u32_e32 v17, v17, v6
	v_add_u32_e32 v17, v17, v7
	v_add_u32_e32 v17, v17, v8
	v_add_u32_e32 v17, v17, v9
	v_add_u32_e32 v17, v17, v10
	v_add_u32_e32 v17, v17, v11
	s_waitcnt vmcnt(4)
	v_add_u32_e32 v17, v17, v12
	s_waitcnt vmcnt(3)
	v_add_u32_e32 v17, v17, v13
	s_waitcnt vmcnt(2)
	v_add_u32_e32 v17, v17, v14
	s_waitcnt vmcnt(1)
	v_add_u32_e32 v17, v17, v15
	s_waitcnt vmcnt(0)
	v_add_u32_e32 v17, v17, v16
	v_cmp_eq_u32_e32 vcc, s33, v17
	s_cbranch_vccnz .LBB0_253
	s_and_b32 s6, s14, 0xff
	s_cmp_eq_u32 s6, 0
	s_mov_b64 s[6:7], -1
	s_mov_b64 s[12:13], -1
	s_sleep 1
	s_cbranch_scc1 .LBB0_258
	s_and_b64 vcc, exec, s[12:13]
	s_cbranch_vccz .LBB0_253

.LBB0_663:
	v_readlane_b32 s6, v253, 13
	v_readlane_b32 s7, v253, 14
	global_load_dword v0, v1, s[36:37] sc1
	s_mov_b64 s[8:9], -1
	s_waitcnt lgkmcnt(0)
	s_nop 1
	global_load_dword v2, v1, s[6:7] sc1
	v_readlane_b32 s6, v253, 15
	v_readlane_b32 s7, v253, 16
	s_nop 4
	global_load_dword v3, v1, s[6:7] sc1
	v_readlane_b32 s6, v253, 17
	v_readlane_b32 s7, v253, 18
	s_nop 4
	global_load_dword v4, v1, s[6:7] sc1
	v_readlane_b32 s6, v253, 19
	v_readlane_b32 s7, v253, 20
	s_nop 4
	global_load_dword v5, v1, s[6:7] sc1
	v_readlane_b32 s6, v253, 21
	v_readlane_b32 s7, v253, 22
	s_nop 4
	global_load_dword v6, v1, s[6:7] sc1
	v_readlane_b32 s6, v253, 23
	v_readlane_b32 s7, v253, 24
	s_nop 4
	global_load_dword v7, v1, s[6:7] sc1
	v_readlane_b32 s6, v253, 25
	v_readlane_b32 s7, v253, 26
	s_nop 4
	global_load_dword v8, v1, s[6:7] sc1
	v_readlane_b32 s6, v253, 27
	v_readlane_b32 s7, v253, 28
	s_nop 4
	global_load_dword v9, v1, s[6:7] sc1
	v_readlane_b32 s6, v253, 29
	v_readlane_b32 s7, v253, 30
	s_nop 4
	global_load_dword v10, v1, s[6:7] sc1
	v_readlane_b32 s6, v253, 31
	v_readlane_b32 s7, v253, 32
	s_nop 4
	global_load_dword v11, v1, s[6:7] sc1
	v_readlane_b32 s6, v253, 33
	v_readlane_b32 s7, v253, 34
	s_nop 4
	global_load_dword v12, v1, s[6:7] sc1
	v_readlane_b32 s6, v253, 35
	v_readlane_b32 s7, v253, 36
	s_nop 4
	global_load_dword v13, v1, s[6:7] sc1
	global_load_dword v14, v1, s[90:91] sc1
	global_load_dword v15, v1, s[92:93] sc1
	global_load_dword v16, v1, s[94:95] sc1
	s_mov_b64 s[6:7], -1
	s_waitcnt vmcnt(5)
	v_add_u32_e32 v17, v2, v0
	v_add_u32_e32 v17, v17, v3
	v_add_u32_e32 v17, v17, v4
	v_add_u32_e32 v17, v17, v5
	v_add_u32_e32 v17, v17, v6
	v_add_u32_e32 v17, v17, v7
	v_add_u32_e32 v17, v17, v8
	v_add_u32_e32 v17, v17, v9
	v_add_u32_e32 v17, v17, v10
	v_add_u32_e32 v17, v17, v11
	s_waitcnt vmcnt(4)
	v_add_u32_e32 v17, v17, v12
	s_waitcnt vmcnt(3)
	v_add_u32_e32 v17, v17, v13
	s_waitcnt vmcnt(2)
	v_add_u32_e32 v17, v17, v14
	s_waitcnt vmcnt(1)
	v_add_u32_e32 v17, v17, v15
	s_waitcnt vmcnt(0)
	v_add_u32_e32 v17, v17, v16
	v_cmp_eq_u32_e32 vcc, s33, v17
	s_cbranch_vccnz .LBB0_662
	s_and_b32 s6, s14, 0xff
	s_cmp_eq_u32 s6, 0
	s_mov_b64 s[6:7], -1
	s_mov_b64 s[12:13], -1
	s_sleep 1
	s_cbranch_scc1 .LBB0_667
	s_and_b64 vcc, exec, s[12:13]
	s_cbranch_vccz .LBB0_662

.LBB0_1296:
	v_readlane_b32 s6, v253, 13
	v_readlane_b32 s7, v253, 14
	global_load_dword v0, v1, s[22:23] sc1
	s_mov_b64 s[8:9], -1
	s_waitcnt lgkmcnt(0)
	s_nop 1
	global_load_dword v2, v1, s[6:7] sc1
	v_readlane_b32 s6, v253, 15
	v_readlane_b32 s7, v253, 16
	s_nop 4
	global_load_dword v3, v1, s[6:7] sc1
	v_readlane_b32 s6, v253, 17
	v_readlane_b32 s7, v253, 18
	s_nop 4
	global_load_dword v4, v1, s[6:7] sc1
	v_readlane_b32 s6, v253, 19
	v_readlane_b32 s7, v253, 20
	s_nop 4
	global_load_dword v5, v1, s[6:7] sc1
	v_readlane_b32 s6, v253, 21
	v_readlane_b32 s7, v253, 22
	s_nop 4
	global_load_dword v6, v1, s[6:7] sc1
	v_readlane_b32 s6, v253, 23
	v_readlane_b32 s7, v253, 24
	s_nop 4
	global_load_dword v7, v1, s[6:7] sc1
	v_readlane_b32 s6, v253, 25
	v_readlane_b32 s7, v253, 26
	s_nop 4
	global_load_dword v8, v1, s[6:7] sc1
	v_readlane_b32 s6, v253, 27
	v_readlane_b32 s7, v253, 28
	s_nop 4
	global_load_dword v9, v1, s[6:7] sc1
	v_readlane_b32 s6, v253, 29
	v_readlane_b32 s7, v253, 30
	s_nop 4
	global_load_dword v10, v1, s[6:7] sc1
	v_readlane_b32 s6, v253, 31
	v_readlane_b32 s7, v253, 32
	s_nop 4
	global_load_dword v11, v1, s[6:7] sc1
	v_readlane_b32 s6, v253, 33
	v_readlane_b32 s7, v253, 34
	s_nop 4
	global_load_dword v12, v1, s[6:7] sc1
	v_readlane_b32 s6, v253, 35
	v_readlane_b32 s7, v253, 36
	s_nop 4
	global_load_dword v13, v1, s[6:7] sc1
	global_load_dword v14, v1, s[90:91] sc1
	global_load_dword v15, v1, s[92:93] sc1
	global_load_dword v16, v1, s[94:95] sc1
	s_mov_b64 s[6:7], -1
	s_waitcnt vmcnt(5)
	v_add_u32_e32 v17, v2, v0
	v_add_u32_e32 v17, v17, v3
	v_add_u32_e32 v17, v17, v4
	v_add_u32_e32 v17, v17, v5
	v_add_u32_e32 v17, v17, v6
	v_add_u32_e32 v17, v17, v7
	v_add_u32_e32 v17, v17, v8
	v_add_u32_e32 v17, v17, v9
	v_add_u32_e32 v17, v17, v10
	v_add_u32_e32 v17, v17, v11
	s_waitcnt vmcnt(4)
	v_add_u32_e32 v17, v17, v12
	s_waitcnt vmcnt(3)
	v_add_u32_e32 v17, v17, v13
	s_waitcnt vmcnt(2)
	v_add_u32_e32 v17, v17, v14
	s_waitcnt vmcnt(1)
	v_add_u32_e32 v17, v17, v15
	s_waitcnt vmcnt(0)
	v_add_u32_e32 v17, v17, v16
	v_cmp_eq_u32_e32 vcc, s33, v17
	s_cbranch_vccnz .LBB0_1295
	s_and_b32 s6, s14, 0xff
	s_cmp_eq_u32 s6, 0
	s_mov_b64 s[6:7], -1
	s_mov_b64 s[12:13], -1
	s_sleep 1
	s_cbranch_scc1 .LBB0_1300
	s_and_b64 vcc, exec, s[12:13]
	s_cbranch_vccz .LBB0_1295
